# attention tile loop: K/V tile loads use SGPR base + loop-invariant 32-bit VGPR offsets
# speedup vs baseline: 1.0121x; 1.0049x over previous
; #define LAS __attribute__((address_space(3)))
; DEV void attn_item(LAS unsigned char* lds, const bf16_t* P, const bf16_t* QB, const bf16_t* KV, const bf16_t* KC, const bf16_t* VC, const float* rel_bias, bf16_t* OB, int b, int g, int qt) {
;     ...
;         const int cur = qt;
;         const unsigned forced = 1u | (1u << cur) | (cur > 0 ? (1u << (cur - 1)) : 0u);
;         const int need = 8 - __popc(forced);
;         for (int it = 0; it < 4; ++it) { const int q = wave * 8 + it * 2 + (lane >> 5), j = lane & 31;
;             const float v = IMPF[q * 32 + j]; int rank = 0;
;             for (int jp = 1; jp <= cur - 2; ++jp) { const float vp = IMPF[q * 32 + jp]; rank += (vp > v || (vp == v && jp < j)) ? 1 : 0; }
;             const bool sel = (j >= 1) && (j <= cur - 2) && (rank < need);
;             const unsigned long long bal = __ballot(sel);
;             const unsigned mq = forced | (unsigned)(lane < 32 ? bal : (bal >> 32));
;             if (j == 0) MASK[q] = mq; }
;     }
;     __syncthreads();
;     const unsigned mymask = MASK[qs * 16 + fr];
;     unsigned anym = MASK[lane];
; #pragma unroll
;     for (int o = 32; o >= 1; o >>= 1) anym |= __shfl_xor(anym, o);
;     anym = __builtin_amdgcn_readfirstlane(anym);
;     {
;         float cbias[2]; cbias[0] = *(const LAS float*)(lds + btb + 512); cbias[1] = *(const LAS float*)(lds + btb + 512 + 516);
;         float mrun[2] = {NEG_, NEG_}, lrun[2] = {0.f, 0.f}; f32x4 O[2][4];
; #pragma unroll
;         for (int hh = 0; hh < 2; ++hh)
; #pragma unroll
;             for (int dt = 0; dt < 4; ++dt) O[hh][dt] = (f32x4){0.f, 0.f, 0.f, 0.f};
;         unsigned rem = anym & (qt >= 31 ? 0xffffffffu : ((2u << qt) - 1u)); rem &= ~1u;
;         int mode = 1, j = 0, buf = 0;
;         for (;;) {
;             kv_store(lds, pre, buf, tid);
.Lrk_done:
	s_lshr_b32 s4, 0x80000000, s17
	s_lshl_b32 s5, 1, s64
	s_cmp_lg_u32 s17, 31
	s_cselect_b32 s5, s5, 0
	s_or_b32 s4, s4, s5
	s_or_b32 s92, s4, 1
	s_bcnt1_i32_b32 s4, s92
	s_sub_i32 s93, 8, s4
	v_cmp_ne_u32_e32 vcc, 0, v60
	v_cmp_ge_i32_e64 s[44:45], s36, v60
	v_and_b32_e32 v67, 32, v150
	v_lshl_add_u32 v68, v66, 2, 0
	s_and_b64 s[4:5], vcc, s[44:45]
	v_add_u32_e32 v68, 0x11c00, v68
	v_cmp_eq_u32_e64 s[42:43], 0, v60
	v_cmp_gt_i32_e32 vcc, s93, v74
	s_and_b64 vcc, s[4:5], vcc
	s_nop 0
	v_lshrrev_b64 v[78:79], v67, vcc
	v_or_b32_e32 v78, s92, v78
	v_cmp_gt_i32_e32 vcc, s93, v75
	s_and_b64 vcc, s[4:5], vcc
	s_nop 0
	v_lshrrev_b64 v[80:81], v67, vcc
	v_or_b32_e32 v80, s92, v80
	v_cmp_gt_i32_e32 vcc, s93, v76
	s_and_b64 vcc, s[4:5], vcc
	s_nop 0
	v_lshrrev_b64 v[82:83], v67, vcc
	v_or_b32_e32 v82, s92, v82
	v_cmp_gt_i32_e32 vcc, s93, v77
	s_and_b64 vcc, s[4:5], vcc
	s_nop 0
	v_lshrrev_b64 v[84:85], v67, vcc
	v_or_b32_e32 v84, s92, v84
	s_and_saveexec_b64 s[4:5], s[42:43]
	ds_write_b32 v68, v78
	ds_write_b32 v68, v80 offset:8
	ds_write_b32 v68, v82 offset:16
	ds_write_b32 v68, v84 offset:24
	s_or_b64 exec, exec, s[4:5]
	s_add_i32 s4, 0, 0x11c00
	v_lshl_add_u32 v7, v152, 2, s4
	s_waitcnt lgkmcnt(0)
	s_barrier
	ds_read_b32 v7, v7
	v_lshlrev_b32_e32 v60, 2, v137
	v_lshlrev_b32_e32 v61, 2, v136
	v_add3_u32 v60, s4, v60, v61
	ds_read_b32 v127, v60
	s_waitcnt lgkmcnt(1)
	ds_bpermute_b32 v61, v144, v7
	v_and_b32_e32 v60, 0xffff0000, v149
	v_lshlrev_b32_e32 v126, 16, v149
	s_lshl_b32 s5, 2, s15
	s_waitcnt lgkmcnt(1)
	v_pk_fma_f32 v[134:135], v[126:127], v[2:3], 0 op_sel_hi:[0,1,0]
	s_waitcnt lgkmcnt(0)
	v_or_b32_e32 v7, v61, v7
	v_pk_fma_f32 v[116:117], v[60:61], v[44:45], 0 op_sel_hi:[0,1,0]
	ds_bpermute_b32 v44, v143, v7
	v_xor_b32_e32 v3, 4, v213
	v_pk_fma_f32 v[130:131], v[126:127], v[4:5], 0 op_sel_hi:[0,1,0]
	v_pk_fma_f32 v[132:133], v[126:127], v[32:33], 0 op_sel_hi:[0,1,0]
	s_add_i32 s5, s5, -1
	s_waitcnt lgkmcnt(0)
	v_or_b32_e32 v7, v44, v7
	v_xor_b32_e32 v44, 8, v213
	v_cmp_lt_i32_e32 vcc, v44, v153
	s_and_b32 s5, s5, -2
	s_cmp_lt_u32 s15, 31
	v_cndmask_b32_e32 v44, v213, v44, vcc
	v_lshlrev_b32_e32 v44, 2, v44
	ds_bpermute_b32 v44, v44, v7
	v_cmp_lt_i32_e32 vcc, v3, v153
	s_cselect_b32 s5, s5, -2
	v_pk_fma_f32 v[114:115], v[60:61], v[46:47], 0 op_sel_hi:[0,1,0]
	v_cndmask_b32_e32 v3, v213, v3, vcc
	s_waitcnt lgkmcnt(0)
	v_or_b32_e32 v2, v44, v7
	v_lshlrev_b32_e32 v3, 2, v3
	ds_bpermute_b32 v3, v3, v2
	v_pk_fma_f32 v[110:111], v[60:61], v[50:51], 0 op_sel_hi:[0,1,0]
	v_pk_fma_f32 v[112:113], v[60:61], v[48:49], 0 op_sel_hi:[0,1,0]
	v_pk_fma_f32 v[104:105], v[60:61], v[54:55], 0 op_sel_hi:[0,1,0]
	v_pk_fma_f32 v[108:109], v[60:61], v[52:53], 0 op_sel_hi:[0,1,0]
	s_waitcnt lgkmcnt(0)
	v_or_b32_e32 v4, v3, v2
	v_xor_b32_e32 v2, 2, v213
	v_cmp_lt_i32_e32 vcc, v2, v153
	v_and_b32_e32 v3, 0xffff0000, v148
	v_pk_fma_f32 v[102:103], v[60:61], v[58:59], 0 op_sel_hi:[0,1,0]
	v_cndmask_b32_e32 v2, v213, v2, vcc
	v_lshlrev_b32_e32 v2, 2, v2
	ds_bpermute_b32 v5, v2, v4
	v_lshlrev_b32_e32 v2, 16, v148
	v_mov_b32_e32 v148, 0
	v_pk_fma_f32 v[106:107], v[60:61], v[56:57], 0 op_sel_hi:[0,1,0]
	v_pk_fma_f32 v[128:129], v[126:127], v[34:35], 0 op_sel_hi:[0,1,0]
	s_waitcnt lgkmcnt(0)
	v_or_b32_e32 v32, v5, v4
	v_xor_b32_e32 v4, 1, v213
	v_cmp_lt_i32_e32 vcc, v4, v153
	v_pk_fma_f32 v[120:121], v[126:127], v[38:39], 0 op_sel_hi:[0,1,0]
	v_pk_fma_f32 v[124:125], v[126:127], v[36:37], 0 op_sel_hi:[0,1,0]
	v_cndmask_b32_e32 v4, v213, v4, vcc
	v_lshlrev_b32_e32 v4, 2, v4
	ds_bpermute_b32 v33, v4, v32
	v_pk_fma_f32 v[118:119], v[126:127], v[42:43], 0 op_sel_hi:[0,1,0]
	v_pk_fma_f32 v[122:123], v[126:127], v[40:41], 0 op_sel_hi:[0,1,0]
	v_and_b32_e32 v5, 0xffff0000, v147
	v_lshlrev_b32_e32 v4, 16, v147
	s_waitcnt lgkmcnt(0)
	v_or_b32_e32 v32, v33, v32
	v_add_u32_e32 v33, 0x200, v142
	ds_read2_b32 v[136:137], v33 offset1:129
	v_readfirstlane_b32 s4, v32
	v_mul_lo_u32 v32, v100, s24
	v_or_b32_e32 v32, v32, v152
	v_lshl_add_u32 v146, v32, 1, v221
	v_sub_u32_e64 v32, s15, 8 clamp
	v_mov_b32_e32 v7, v60
	s_mov_b32 s97, 1
	s_and_b32 s95, s4, s5
	v_readfirstlane_b32 s94, v32
	s_sub_i32 s17, 23, s17
	v_add_u32_e32 v145, 0, v145
	s_mov_b32 s50, 0
	v_mov_b32_e32 v150, 0xf149f2ca
	v_mov_b32_e32 v147, 0
	v_mov_b32_e32 v149, 0xf149f2ca
	v_mov_b32_e32 v151, 0
	v_mov_b32_e32 v48, 0
	v_mov_b32_e32 v49, v148
	v_mov_b32_e32 v50, v148
	v_mov_b32_e32 v51, v148
	v_mov_b32_e32 v36, 0
	v_mov_b32_e32 v37, v148
	v_mov_b32_e32 v38, v148
	v_mov_b32_e32 v39, v148
	v_mov_b32_e32 v40, 0
	v_mov_b32_e32 v41, v148
	v_mov_b32_e32 v42, v148
	v_mov_b32_e32 v43, v148
	v_mov_b32_e32 v32, 0
	v_mov_b32_e32 v33, v148
	v_mov_b32_e32 v34, v148
	v_mov_b32_e32 v35, v148
	v_mov_b32_e32 v60, 0
	v_mov_b32_e32 v61, v148
	v_mov_b32_e32 v62, v148
	v_mov_b32_e32 v63, v148
	v_mov_b32_e32 v52, 0
	v_mov_b32_e32 v53, v148
	v_mov_b32_e32 v54, v148
	v_mov_b32_e32 v55, v148
	v_mov_b32_e32 v56, 0
	v_mov_b32_e32 v57, v148
	v_mov_b32_e32 v58, v148
	v_mov_b32_e32 v59, v148
	v_mov_b32_e32 v44, 0
	v_mov_b32_e32 v45, v148
	v_mov_b32_e32 v46, v148
	v_mov_b32_e32 v47, v148
	v_lshlrev_b32_e32 v192, 1, v98
	v_lshl_add_u32 v193, v100, 1, v0
	v_readfirstlane_b32 s100, v210
	s_mov_b32 s98, 0
	s_waitcnt vmcnt(1)
	ds_write_b128 v139, v[24:27]
	s_waitcnt vmcnt(0)
	ds_write_b16 v146, v28
	ds_write_b16_d16_hi v146, v28 offset:144
	ds_write_b16 v146, v29 offset:288
	ds_write_b16_d16_hi v146, v29 offset:432
	ds_write_b16 v146, v30 offset:576
	ds_write_b16_d16_hi v146, v30 offset:720
	ds_write_b16 v146, v31 offset:864
	ds_write_b16_d16_hi v146, v31 offset:1008
	s_lshr_b32 s100, s100, 8
	s_mul_i32 s100, s100, 3
	s_waitcnt lgkmcnt(0)
	s_barrier

; DEV void attn_item(LAS unsigned char* lds, const bf16_t* P, const bf16_t* QB, const bf16_t* KV, const bf16_t* KC, const bf16_t* VC, const float* rel_bias, bf16_t* OB, int b, int g, int qt) {
;     ...
;             if (mode == 1) { if (rem != 0u) { j_n = __builtin_ctz(rem); rem &= rem - 1u; } else { mode_n = 2; j_n = max(0, qt - 8); } }
;             else { j_n = j + 1; more = j_n <= qt; }
;             if (more) { const bf16_t* base = pbg + (size_t)j_n * 64 * 64 + (mode_n == 1 ? 2 : 4) * KV_TENSOR; pre = kv_fetch(base, base + KV_TENSOR, tid); }
.LBB0_268:
	s_ashr_i32 s53, s52, 31
	s_lshl_b64 s[6:7], s[52:53], 13
	s_add_u32 s5, s90, s6
	s_addc_u32 s6, s91, s7
	s_lshl_b32 s4, s4, 1
	s_add_u32 s4, s5, s4
	s_addc_u32 s5, s6, 0
	s_add_u32 s6, s4, 0x800000
	s_addc_u32 s7, s5, 0
	global_load_dwordx4 v[24:27], v192, s[4:5]
	global_load_dwordx4 v[28:31], v193, s[6:7]
